# v084 + conversion of the layer-1 FFN weights (gate/up/down L1) moved out of P0 into the idle tails of the layer-0 gate/up and down GEMM phases (workgroups without a last-round tile)
# speedup vs baseline: 1.0132x; 1.0088x over previous
; #define LAS __attribute__((address_space(3)))
; __device__ __forceinline__ void p0_weights(KAP a, LAS unsigned char* lds, int gw, int NGW, int wave, int lane) {
;     LAS float* scr = (LAS float*)(lds + wave * 8704);
;     unsigned char* ws = a->ws;
;     constexpr int I_TOTAL = (2048 / 64) * (2624 / 32) + (512 / 64) * (1536 / 32) + (512 / 64) * (2048 / 32) + 2 * (2048 / 64) * (2048 / 32) + (2048 / 64) * (4608 / 32)
;                           + 4 * (2048 / 64) * (DFF / 32) + 2 * (DFF / 64) * (2048 / 32);
;     for (int item = gw; item < I_TOTAL; item += NGW) {
;         int it = item;
;         if (conv_matrix(it, a->in[13], 2048, 2624, (bf16*)(ws + WS_WIN0), 0, scr, lane)) continue;
;         if (conv_matrix(it, a->in[19], 512, 1536, (bf16*)(ws + WS_WUQ), 0, scr, lane, 0.07216878364870322f * 1.4426950408889634f)) continue;
;         if (conv_matrix(it, a->in[20], 512, 2048, (bf16*)(ws + WS_WUKV), 0, scr, lane)) continue;
;         if (conv_matrix(it, a->in[14], 2048, 2048, (bf16*)(ws + WS_WOUT0), 0, scr, lane)) continue;
;         if (conv_matrix(it, a->in[21], 2048, 4608, (bf16*)(ws + WS_WIN1), 0, scr, lane)) continue;
;         if (conv_matrix(it, a->in[22], 2048, 2048, (bf16*)(ws + WS_WOUT1), 0, scr, lane)) continue;
;         if (conv_matrix(it, a->in[10], 2048, DFF, (bf16*)(ws + WS_WGU), 1, scr, lane)) continue;
;         if (conv_matrix(it, a->in[10] + (size_t)2048 * DFF, 2048, DFF, (bf16*)(ws + WS_WGU + 44 * MiB), 1, scr, lane)) continue;
;         if (conv_matrix(it, a->in[11], 2048, DFF, (bf16*)(ws + WS_WGU), 2, scr, lane)) continue;
;         if (conv_matrix(it, a->in[11] + (size_t)2048 * DFF, 2048, DFF, (bf16*)(ws + WS_WGU + 44 * MiB), 2, scr, lane)) continue;
;         if (conv_matrix(it, a->in[12], DFF, 2048, (bf16*)(ws + WS_WD), 0, scr, lane)) continue;
;         conv_matrix(it, a->in[12] + (size_t)2048 * DFF, DFF, 2048, (bf16*)(ws + WS_WD + 22 * MiB), 0, scr, lane);
;     }
; }
.LBB0_36:
	v_mbcnt_lo_u32_b32 v2, -1, 0
	v_mbcnt_hi_u32_b32 v2, -1, v2
	s_lshl_b32 s5, s87, 3
	v_add_u32_e32 v0, s93, v2
	s_lshl_b32 s33, s74, 3
	v_readfirstlane_b32 s4, v0
	s_ashr_i32 s6, s4, 6
	s_add_i32 s99, s6, s5
	v_writelane_b32 v253, s5, 2
	s_mov_b64 s[4:5], s[0:1]
	s_cmp_gt_i32 s99, 0x71bf
	s_cbranch_scc1 .LBB0_119
	s_load_dwordx2 s[8:9], s[4:5], 0xf0
	v_bfe_u32 v0, v2, 5, 1
	v_and_b32_e32 v28, 31, v2
	v_bfe_u32 v1, v2, 3, 3
	v_lshlrev_b32_e32 v2, 3, v2
	v_and_b32_e32 v2, 56, v2
	v_mov_b32_e32 v3, 0
	v_mul_u32_u24_e32 v6, 0x84, v2
	v_lshlrev_b32_e32 v2, 1, v2
	s_mul_i32 s10, s6, 0x2200
	s_waitcnt lgkmcnt(0)
	v_lshl_add_u64 v[22:23], s[8:9], 0, v[2:3]
	s_mov_b64 s[6:7], 0x100000
	s_add_i32 s11, s10, 0
	v_lshl_add_u64 v[4:5], v[22:23], 0, s[6:7]
	v_lshlrev_b32_e32 v2, 2, v1
	s_mov_b64 s[6:7], 0xc00000
	v_add3_u32 v44, s11, v6, v2
	v_lshl_add_u64 v[6:7], v[22:23], 0, s[6:7]
	s_mov_b64 s[6:7], 0xe00000
	v_lshl_add_u64 v[8:9], v[22:23], 0, s[6:7]
	s_mov_b64 s[6:7], 0x1000000
	v_lshl_add_u64 v[10:11], v[22:23], 0, s[6:7]
	s_mov_b64 s[6:7], 0x1800000
	v_lshl_add_u64 v[12:13], v[22:23], 0, s[6:7]
	s_mov_b64 s[6:7], 0x2a00000
	v_lshl_add_u64 v[14:15], v[22:23], 0, s[6:7]
	s_mov_b64 s[6:7], 0x3200000
	v_lshl_add_u64 v[16:17], v[22:23], 0, s[6:7]
	s_mov_b64 s[6:7], 0x5e00000
	v_lshl_add_u64 v[18:19], v[22:23], 0, s[6:7]
	s_mov_b64 s[6:7], 0x8a00000
	v_mul_u32_u24_e32 v2, 0x84, v0
	v_lshl_add_u64 v[20:21], v[22:23], 0, s[6:7]
	s_mov_b64 s[6:7], 0xa000000
	v_or_b32_e32 v2, s10, v2
	v_lshlrev_b32_e32 v24, 2, v28
	v_or_b32_e32 v45, 8, v1
	v_or_b32_e32 v46, 16, v1
	v_or_b32_e32 v47, 24, v1
	v_lshl_add_u64 v[22:23], v[22:23], 0, s[6:7]
	v_add3_u32 v48, v2, v24, 0
	v_mov_b32_e32 v25, v3
	v_or_b32_e32 v49, 14, v0
	v_or_b32_e32 v50, 12, v0
	v_or_b32_e32 v51, 10, v0
	v_or_b32_e32 v52, 8, v0
	v_or_b32_e32 v53, 6, v0
	v_or_b32_e32 v54, 4, v0
	v_or_b32_e32 v55, 2, v0
	v_or_b32_e32 v26, 0x2c00000, v24
	v_mov_b32_e32 v27, v3
	s_movk_i32 s23, 0x2900
	s_movk_i32 s24, 0x7fff
	s_mov_b32 s25, 0xffff0000
	s_movk_i32 s26, 0x1800
	s_movk_i32 s27, 0x4800
	s_movk_i32 s28, 0x1600
	s_movk_i32 s29, 0x5800
	s_mov_b64 s[6:7], 0x2c00000
	v_lshlrev_b32_e32 v2, 2, v28
	v_mov_b32_e32 v56, 0x4800
	v_mov_b32_e32 v57, 0x5800
	s_branch .LBB0_39
.LBB0_38:
	s_add_i32 s99, s99, s33
	s_cmp_lt_i32 s99, 0x71c0
	s_cbranch_scc0 .LBB0_119
.LBB0_39:
	s_mov_b32 s22, s99
	s_cmp_ge_i32 s99, 0x45c0
	s_cselect_b32 s98, 0x1600, 0
	s_add_i32 s22, s22, s98
	s_cmp_ge_i32 s99, 0x5bc0
	s_cselect_b32 s98, 0x1600, 0
	s_add_i32 s22, s22, s98
	s_cmpk_gt_i32 s22, 0xa3f
	s_waitcnt lgkmcnt(0)
	s_cselect_b64 s[8:9], -1, 0
	s_cmpk_lt_i32 s22, 0xa40
	s_mov_b64 s[10:11], -1
	s_cbranch_scc0 .LBB0_42
	s_andn2_b64 vcc, exec, s[10:11]
	s_cbranch_vccz .LBB0_43

; #define PG8_WAIT_V(n) asm volatile("s_waitcnt vmcnt(" #n ")" ::: "memory")
; #define PG8_BAR __builtin_amdgcn_s_barrier()
; #define LAS __attribute__((address_space(3)))
; template <class Epi, class Sched, bool ALIGN_EPI = false, bool SP2 = false>
; __device__ __forceinline__ void gemm_phase(PG8_LAS unsigned char* lds, const Gemm g, const Sched& S, const Epi& E, const int wave0) {
;     ...
;     PG8_WAIT_V(0);
;     if constexpr (!ALIGN_EPI) { if (wr == 0) PG8_BAR; }
;     PG8_BAR;
; __device__ __forceinline__ void p0_weights(KAP a, LAS unsigned char* lds, int gw, int NGW, int wave, int lane) {
;     LAS float* scr = (LAS float*)(lds + wave * 8704);
;     unsigned char* ws = a->ws;
;     constexpr int I_TOTAL = (2048 / 64) * (2624 / 32) + (512 / 64) * (1536 / 32) + (512 / 64) * (2048 / 32) + 2 * (2048 / 64) * (2048 / 32) + (2048 / 64) * (4608 / 32)
;                           + 4 * (2048 / 64) * (DFF / 32) + 2 * (DFF / 64) * (2048 / 32);
;     for (int item = gw; item < I_TOTAL; item += NGW) {
;         int it = item;
;         if (conv_matrix(it, a->in[13], 2048, 2624, (bf16*)(ws + WS_WIN0), 0, scr, lane)) continue;
;         if (conv_matrix(it, a->in[19], 512, 1536, (bf16*)(ws + WS_WUQ), 0, scr, lane, 0.07216878364870322f * 1.4426950408889634f)) continue;
;         if (conv_matrix(it, a->in[20], 512, 2048, (bf16*)(ws + WS_WUKV), 0, scr, lane)) continue;
;         if (conv_matrix(it, a->in[14], 2048, 2048, (bf16*)(ws + WS_WOUT0), 0, scr, lane)) continue;
;         if (conv_matrix(it, a->in[21], 2048, 4608, (bf16*)(ws + WS_WIN1), 0, scr, lane)) continue;
;         if (conv_matrix(it, a->in[22], 2048, 2048, (bf16*)(ws + WS_WOUT1), 0, scr, lane)) continue;
;         if (conv_matrix(it, a->in[10], 2048, DFF, (bf16*)(ws + WS_WGU), 1, scr, lane)) continue;
;         if (conv_matrix(it, a->in[10] + (size_t)2048 * DFF, 2048, DFF, (bf16*)(ws + WS_WGU + 44 * MiB), 1, scr, lane)) continue;
;         if (conv_matrix(it, a->in[11], 2048, DFF, (bf16*)(ws + WS_WGU), 2, scr, lane)) continue;
;         if (conv_matrix(it, a->in[11] + (size_t)2048 * DFF, 2048, DFF, (bf16*)(ws + WS_WGU + 44 * MiB), 2, scr, lane)) continue;
;         if (conv_matrix(it, a->in[12], DFF, 2048, (bf16*)(ws + WS_WD), 0, scr, lane)) continue;
;         conv_matrix(it, a->in[12] + (size_t)2048 * DFF, DFF, 2048, (bf16*)(ws + WS_WD + 22 * MiB), 0, scr, lane);
;     }
; }
.LBB0_1042:
	s_waitcnt vmcnt(0)
	v_readlane_b32 s48, v254, 50
	v_readlane_b32 s49, v254, 51
	s_movk_i32 s89, 0xffef
	s_movk_i32 s91, 0xffe0
	s_movk_i32 s92, 0xffd0
	s_barrier
	v_readlane_b32 s4, v254, 52
	s_nop 1
	s_cmp_lg_u32 s4, 0
	s_cbranch_scc1 .Ldfa_skip
	s_cmp_lt_u32 s87, 88
	s_cbranch_scc1 .Ldfa_skip
	v_mov_b32_e32 v250, v3
	v_writelane_b32 v255, s10, 10
	v_writelane_b32 v255, s12, 11
	v_writelane_b32 v255, s13, 12
	v_writelane_b32 v255, s14, 13
	v_writelane_b32 v255, s15, 14
	v_writelane_b32 v255, s22, 15
	v_writelane_b32 v255, s23, 16
	v_writelane_b32 v255, s24, 17
	v_writelane_b32 v255, s25, 18
	v_writelane_b32 v255, s26, 19
	v_writelane_b32 v255, s27, 20
	v_writelane_b32 v255, s28, 21
	v_writelane_b32 v255, s29, 22
	v_writelane_b32 v255, s31, 23
	v_writelane_b32 v255, s33, 24
.Ldfa_36:
	v_mbcnt_lo_u32_b32 v2, -1, 0
	v_mbcnt_hi_u32_b32 v2, -1, v2
	s_sub_i32 s5, s87, 88
	s_lshl_b32 s5, s5, 3
	s_add_i32 s5, s5, 0x0
	v_readlane_b32 s4, v254, 48
	s_nop 1
	v_add_u32_e32 v0, s4, v2
	s_movk_i32 s33, 0x540
	v_readfirstlane_b32 s4, v0
	s_ashr_i32 s6, s4, 6
	s_add_i32 s99, s6, s5
	s_mov_b64 s[4:5], s[0:1]
	s_cmp_gt_i32 s99, 0x24bf
	s_cbranch_scc1 .Ldfa_exit
	s_load_dwordx2 s[8:9], s[4:5], 0xf0
	v_bfe_u32 v0, v2, 5, 1
	v_and_b32_e32 v28, 31, v2
	v_bfe_u32 v1, v2, 3, 3
	v_lshlrev_b32_e32 v2, 3, v2
	v_and_b32_e32 v2, 56, v2
	v_mov_b32_e32 v3, 0
	v_mul_u32_u24_e32 v6, 0x84, v2
	v_lshlrev_b32_e32 v2, 1, v2
	s_mul_i32 s10, s6, 0x2200
	s_waitcnt lgkmcnt(0)
	v_lshl_add_u64 v[22:23], s[8:9], 0, v[2:3]
	s_mov_b64 s[6:7], 0x100000
	s_add_i32 s11, s10, 0
	v_lshl_add_u64 v[4:5], v[22:23], 0, s[6:7]
	v_lshlrev_b32_e32 v2, 2, v1
	s_mov_b64 s[6:7], 0xc00000
	v_add3_u32 v44, s11, v6, v2
	v_lshl_add_u64 v[6:7], v[22:23], 0, s[6:7]
	s_mov_b64 s[6:7], 0xe00000
	v_lshl_add_u64 v[8:9], v[22:23], 0, s[6:7]
	s_mov_b64 s[6:7], 0x1000000
	v_lshl_add_u64 v[10:11], v[22:23], 0, s[6:7]
	s_mov_b64 s[6:7], 0x1800000
	v_lshl_add_u64 v[12:13], v[22:23], 0, s[6:7]
	s_mov_b64 s[6:7], 0x2a00000
	v_lshl_add_u64 v[14:15], v[22:23], 0, s[6:7]
	s_mov_b64 s[6:7], 0x3200000
	v_lshl_add_u64 v[16:17], v[22:23], 0, s[6:7]
	s_mov_b64 s[6:7], 0x5e00000
	v_lshl_add_u64 v[18:19], v[22:23], 0, s[6:7]
	s_mov_b64 s[6:7], 0x8a00000
	v_mul_u32_u24_e32 v2, 0x84, v0
	v_lshl_add_u64 v[20:21], v[22:23], 0, s[6:7]
	s_mov_b64 s[6:7], 0xa000000
	v_or_b32_e32 v2, s10, v2
	v_lshlrev_b32_e32 v24, 2, v28
	v_or_b32_e32 v45, 8, v1
	v_or_b32_e32 v46, 16, v1
	v_or_b32_e32 v47, 24, v1
	v_lshl_add_u64 v[22:23], v[22:23], 0, s[6:7]
	v_add3_u32 v48, v2, v24, 0
	v_mov_b32_e32 v25, v3
	v_or_b32_e32 v49, 14, v0
	v_or_b32_e32 v50, 12, v0
	v_or_b32_e32 v51, 10, v0
	v_or_b32_e32 v52, 8, v0
	v_or_b32_e32 v53, 6, v0
	v_or_b32_e32 v54, 4, v0
	v_or_b32_e32 v55, 2, v0
	v_or_b32_e32 v26, 0x2c00000, v24
	v_mov_b32_e32 v27, v3
	s_movk_i32 s23, 0x2900
	s_movk_i32 s24, 0x7fff
	s_mov_b32 s25, 0xffff0000
	s_movk_i32 s26, 0x1800
	s_movk_i32 s27, 0x4800
	s_movk_i32 s28, 0x1600
	s_movk_i32 s29, 0x5800
	s_mov_b64 s[6:7], 0x2c00000
	v_lshlrev_b32_e32 v2, 2, v28
	v_mov_b32_e32 v56, 0x4800
	v_mov_b32_e32 v57, 0x5800
	s_branch .Ldfa_39
.Ldfa_38:
	s_add_i32 s99, s99, s33
	s_cmp_lt_i32 s99, 0x24c0
	s_cbranch_scc0 .Ldfa_exit
.Ldfa_39:
	s_add_i32 s22, s99, 0x45c0
	s_cmp_ge_i32 s99, 0x1600
	s_cselect_b32 s98, 0x1600, 0
	s_add_i32 s22, s22, s98
	s_cmp_ge_i32 s99, 0x2c00
	s_cselect_b32 s98, 0x1600, 0
	s_add_i32 s22, s22, s98
	s_cmpk_gt_i32 s22, 0xa3f
	s_waitcnt lgkmcnt(0)
	s_cselect_b64 s[8:9], -1, 0
	s_cmpk_lt_i32 s22, 0xa40
	s_mov_b64 s[10:11], -1
	s_cbranch_scc0 .Ldfa_42
	s_andn2_b64 vcc, exec, s[10:11]
	s_cbranch_vccz .Ldfa_43

; __device__ __forceinline__ unsigned xb_add(unsigned* p, unsigned v) { return __hip_atomic_fetch_add(p, v, __ATOMIC_RELAXED, __HIP_MEMORY_SCOPE_AGENT); }
; __device__ __forceinline__ void xcd_barrier(const XcdBarrier& b) {
;     asm volatile("s_waitcnt vmcnt(0)" ::: "memory");
;     __syncthreads();
;     if (threadIdx.x == 0) {
;         unsigned* bar = b.bar;
;         __builtin_amdgcn_s_waitcnt(0);
;         unsigned nloc = b.st[0], nx = b.st[1];
;         if (nloc == 0u) { xcd_barrier_complete(bar, b.x, nloc, nx); b.st[0] = nloc; b.st[1] = nx; }
;         const unsigned old = xb_add(&bar[XB_XSUB(b.x)], 1u);
;         const unsigned gen = old / nloc;
.Ldfa_exit:
	v_readlane_b32 s10, v255, 10
	v_readlane_b32 s12, v255, 11
	v_readlane_b32 s13, v255, 12
	v_readlane_b32 s14, v255, 13
	v_readlane_b32 s15, v255, 14
	v_readlane_b32 s22, v255, 15
	v_readlane_b32 s23, v255, 16
	v_readlane_b32 s24, v255, 17
	v_readlane_b32 s25, v255, 18
	v_readlane_b32 s26, v255, 19
	v_readlane_b32 s27, v255, 20
	v_readlane_b32 s28, v255, 21
	v_readlane_b32 s29, v255, 22
	v_readlane_b32 s31, v255, 23
	v_readlane_b32 s33, v255, 24
	v_mov_b32_e32 v3, v250
	s_nop 3
.Ldfa_skip:
.LBB0_1043:
	s_waitcnt vmcnt(0)
	s_barrier
	s_mov_b64 s[16:17], exec
	v_readlane_b32 s4, v253, 0
	v_readlane_b32 s5, v253, 1
	s_and_b64 s[4:5], s[16:17], s[4:5]
	s_mov_b64 exec, s[4:5]
	s_cbranch_execz .LBB0_1095
	v_readlane_b32 s2, v254, 37
	s_waitcnt vmcnt(0) expcnt(0) lgkmcnt(0)
	s_nop 0
	v_mov_b32_e32 v0, s2
	ds_read_b32 v2, v0
	v_readlane_b32 s2, v254, 38
	s_waitcnt lgkmcnt(0)
	v_cmp_ne_u32_e32 vcc, 0, v2
	v_mov_b32_e32 v0, s2
	ds_read_b32 v0, v0
	s_cbranch_vccnz .LBB0_1059
	s_mov_b32 s2, 1
	s_branch .LBB0_1047

; #define LAS __attribute__((address_space(3)))
; #define WSB (kargs()->ws)
; __device__ __forceinline__ void p0_weights(KAP a, LAS unsigned char* lds, int gw, int NGW, int wave, int lane) {
;     LAS float* scr = (LAS float*)(lds + wave * 8704);
;     unsigned char* ws = a->ws;
;     constexpr int I_TOTAL = (2048 / 64) * (2624 / 32) + (512 / 64) * (1536 / 32) + (512 / 64) * (2048 / 32) + 2 * (2048 / 64) * (2048 / 32) + (2048 / 64) * (4608 / 32)
;                           + 4 * (2048 / 64) * (DFF / 32) + 2 * (DFF / 64) * (2048 / 32);
;     for (int item = gw; item < I_TOTAL; item += NGW) {
;         int it = item;
;         if (conv_matrix(it, a->in[13], 2048, 2624, (bf16*)(ws + WS_WIN0), 0, scr, lane)) continue;
;         if (conv_matrix(it, a->in[19], 512, 1536, (bf16*)(ws + WS_WUQ), 0, scr, lane, 0.07216878364870322f * 1.4426950408889634f)) continue;
;         if (conv_matrix(it, a->in[20], 512, 2048, (bf16*)(ws + WS_WUKV), 0, scr, lane)) continue;
;         if (conv_matrix(it, a->in[14], 2048, 2048, (bf16*)(ws + WS_WOUT0), 0, scr, lane)) continue;
;         if (conv_matrix(it, a->in[21], 2048, 4608, (bf16*)(ws + WS_WIN1), 0, scr, lane)) continue;
;         if (conv_matrix(it, a->in[22], 2048, 2048, (bf16*)(ws + WS_WOUT1), 0, scr, lane)) continue;
;         if (conv_matrix(it, a->in[10], 2048, DFF, (bf16*)(ws + WS_WGU), 1, scr, lane)) continue;
;         if (conv_matrix(it, a->in[10] + (size_t)2048 * DFF, 2048, DFF, (bf16*)(ws + WS_WGU + 44 * MiB), 1, scr, lane)) continue;
;         if (conv_matrix(it, a->in[11], 2048, DFF, (bf16*)(ws + WS_WGU), 2, scr, lane)) continue;
;         if (conv_matrix(it, a->in[11] + (size_t)2048 * DFF, 2048, DFF, (bf16*)(ws + WS_WGU + 44 * MiB), 2, scr, lane)) continue;
;         if (conv_matrix(it, a->in[12], DFF, 2048, (bf16*)(ws + WS_WD), 0, scr, lane)) continue;
;         conv_matrix(it, a->in[12] + (size_t)2048 * DFF, DFF, 2048, (bf16*)(ws + WS_WD + 22 * MiB), 0, scr, lane);
;     }
; }
; __global__ void __launch_bounds__(NTHR, 2) fwd_megakernel(KArgs args) {
;     ...
;         if (L == 0) { pg8::Gemm g = pg8::mk_gemm(ACT_ + (size_t)MLAT * DFF, (const bf16*)(WSB + WS_WD), 2 * NCTX, 4 * DM, DFF / 4, DFF); g.ldb = DFF; g.nNr = DM / 256;
;           pg8::StaticOrder S; S.init(g.M, g.N, G, (int)blockIdx.x); pg8::EpiF32Split E{FP_, DM, DM / 256, (size_t)2 * NCTX * DM};
.LBB0_1144:
	v_readlane_b32 s4, v254, 52
	s_nop 1
	s_cmp_lg_u32 s4, 0
	s_cbranch_scc1 .Ldfb_skip
	s_cmp_lt_u32 s87, 64
	s_cbranch_scc1 .Ldfb_skip
	v_mov_b32_e32 v250, v3
	v_writelane_b32 v255, s10, 10
	v_writelane_b32 v255, s12, 11
	v_writelane_b32 v255, s13, 12
	v_writelane_b32 v255, s14, 13
	v_writelane_b32 v255, s15, 14
	v_writelane_b32 v255, s22, 15
	v_writelane_b32 v255, s23, 16
	v_writelane_b32 v255, s24, 17
	v_writelane_b32 v255, s25, 18
	v_writelane_b32 v255, s26, 19
	v_writelane_b32 v255, s27, 20
	v_writelane_b32 v255, s28, 21
	v_writelane_b32 v255, s29, 22
	v_writelane_b32 v255, s31, 23
	v_writelane_b32 v255, s33, 24
.Ldfb_36:
	v_mbcnt_lo_u32_b32 v2, -1, 0
	v_mbcnt_hi_u32_b32 v2, -1, v2
	s_sub_i32 s5, s87, 64
	s_lshl_b32 s5, s5, 3
	s_add_i32 s5, s5, 0x24c0
	v_readlane_b32 s4, v254, 48
	s_nop 1
	v_add_u32_e32 v0, s4, v2
	s_movk_i32 s33, 0x600
	v_readfirstlane_b32 s4, v0
	s_ashr_i32 s6, s4, 6
	s_add_i32 s99, s6, s5
	s_mov_b64 s[4:5], s[0:1]
	s_cmp_gt_i32 s99, 0x41ff
	s_cbranch_scc1 .Ldfb_exit
	s_load_dwordx2 s[8:9], s[4:5], 0xf0
	v_bfe_u32 v0, v2, 5, 1
	v_and_b32_e32 v28, 31, v2
	v_bfe_u32 v1, v2, 3, 3
	v_lshlrev_b32_e32 v2, 3, v2
	v_and_b32_e32 v2, 56, v2
	v_mov_b32_e32 v3, 0
	v_mul_u32_u24_e32 v6, 0x84, v2
	v_lshlrev_b32_e32 v2, 1, v2
	s_mul_i32 s10, s6, 0x2200
	s_waitcnt lgkmcnt(0)
	v_lshl_add_u64 v[22:23], s[8:9], 0, v[2:3]
	s_mov_b64 s[6:7], 0x100000
	s_add_i32 s11, s10, 0
	v_lshl_add_u64 v[4:5], v[22:23], 0, s[6:7]
	v_lshlrev_b32_e32 v2, 2, v1
	s_mov_b64 s[6:7], 0xc00000
	v_add3_u32 v44, s11, v6, v2
	v_lshl_add_u64 v[6:7], v[22:23], 0, s[6:7]
	s_mov_b64 s[6:7], 0xe00000
	v_lshl_add_u64 v[8:9], v[22:23], 0, s[6:7]
	s_mov_b64 s[6:7], 0x1000000
	v_lshl_add_u64 v[10:11], v[22:23], 0, s[6:7]
	s_mov_b64 s[6:7], 0x1800000
	v_lshl_add_u64 v[12:13], v[22:23], 0, s[6:7]
	s_mov_b64 s[6:7], 0x2a00000
	v_lshl_add_u64 v[14:15], v[22:23], 0, s[6:7]
	s_mov_b64 s[6:7], 0x3200000
	v_lshl_add_u64 v[16:17], v[22:23], 0, s[6:7]
	s_mov_b64 s[6:7], 0x5e00000
	v_lshl_add_u64 v[18:19], v[22:23], 0, s[6:7]
	s_mov_b64 s[6:7], 0x8a00000
	v_mul_u32_u24_e32 v2, 0x84, v0
	v_lshl_add_u64 v[20:21], v[22:23], 0, s[6:7]
	s_mov_b64 s[6:7], 0xa000000
	v_or_b32_e32 v2, s10, v2
	v_lshlrev_b32_e32 v24, 2, v28
	v_or_b32_e32 v45, 8, v1
	v_or_b32_e32 v46, 16, v1
	v_or_b32_e32 v47, 24, v1
	v_lshl_add_u64 v[22:23], v[22:23], 0, s[6:7]
	v_add3_u32 v48, v2, v24, 0
	v_mov_b32_e32 v25, v3
	v_or_b32_e32 v49, 14, v0
	v_or_b32_e32 v50, 12, v0
	v_or_b32_e32 v51, 10, v0
	v_or_b32_e32 v52, 8, v0
	v_or_b32_e32 v53, 6, v0
	v_or_b32_e32 v54, 4, v0
	v_or_b32_e32 v55, 2, v0
	v_or_b32_e32 v26, 0x2c00000, v24
	v_mov_b32_e32 v27, v3
	s_movk_i32 s23, 0x2900
	s_movk_i32 s24, 0x7fff
	s_mov_b32 s25, 0xffff0000
	s_movk_i32 s26, 0x1800
	s_movk_i32 s27, 0x4800
	s_movk_i32 s28, 0x1600
	s_movk_i32 s29, 0x5800
	s_mov_b64 s[6:7], 0x2c00000
	v_lshlrev_b32_e32 v2, 2, v28
	v_mov_b32_e32 v56, 0x4800
	v_mov_b32_e32 v57, 0x5800
	s_branch .Ldfb_39
.Ldfb_38:
	s_add_i32 s99, s99, s33
	s_cmp_lt_i32 s99, 0x4200
	s_cbranch_scc0 .Ldfb_exit

; #define LAS __attribute__((address_space(3)))
; __global__ void __launch_bounds__(NTHR, 2) fwd_megakernel(KArgs args) {
;     extern __shared__ __attribute__((aligned(16))) unsigned char lds[];
;     cg::grid_group grid = cg::this_grid();
;     LAS unsigned char* ldsl = (LAS unsigned char*)lds;
;     const int wave0 = __builtin_amdgcn_readfirstlane(threadIdx.x >> 6);
;     const int G = gridDim.x, NGW = G * NWAVES;
	.amdhsa_kernel _Z14fwd_megakernel5KArgs
		.amdhsa_group_segment_fixed_size 0
		.amdhsa_private_segment_fixed_size 0
		.amdhsa_kernarg_size 504
		.amdhsa_user_sgpr_count 2
		.amdhsa_user_sgpr_dispatch_ptr 0
		.amdhsa_user_sgpr_queue_ptr 0
		.amdhsa_user_sgpr_kernarg_segment_ptr 1
		.amdhsa_user_sgpr_dispatch_id 0
		.amdhsa_user_sgpr_kernarg_preload_length 0
		.amdhsa_user_sgpr_kernarg_preload_offset 0
		.amdhsa_user_sgpr_private_segment_size 0
		.amdhsa_uses_dynamic_stack 0
		.amdhsa_enable_private_segment 0
		.amdhsa_system_sgpr_workgroup_id_x 1
		.amdhsa_system_sgpr_workgroup_id_y 0
		.amdhsa_system_sgpr_workgroup_id_z 0
		.amdhsa_system_sgpr_workgroup_info 0
		.amdhsa_system_vgpr_workitem_id 2
		.amdhsa_next_free_vgpr 256
		.amdhsa_next_free_sgpr 100
		.amdhsa_accum_offset 256
		.amdhsa_reserve_vcc 1
		.amdhsa_float_round_mode_32 0
		.amdhsa_float_round_mode_16_64 0
		.amdhsa_float_denorm_mode_32 3
		.amdhsa_float_denorm_mode_16_64 3
		.amdhsa_dx10_clamp 1
		.amdhsa_ieee_mode 1
		.amdhsa_fp16_overflow 0
		.amdhsa_tg_split 0
		.amdhsa_exception_fp_ieee_invalid_op 0
		.amdhsa_exception_fp_denorm_src 0
		.amdhsa_exception_fp_ieee_div_zero 0
		.amdhsa_exception_fp_ieee_overflow 0
		.amdhsa_exception_fp_ieee_underflow 0
		.amdhsa_exception_fp_ieee_inexact 0
		.amdhsa_exception_int_div_zero 0
	.end_amdhsa_kernel

; #define LAS __attribute__((address_space(3)))
; __global__ void __launch_bounds__(NTHR, 2) fwd_megakernel(KArgs args) {
;     extern __shared__ __attribute__((aligned(16))) unsigned char lds[];
;     cg::grid_group grid = cg::this_grid();
;     LAS unsigned char* ldsl = (LAS unsigned char*)lds;
;     const int wave0 = __builtin_amdgcn_readfirstlane(threadIdx.x >> 6);
;     const int G = gridDim.x, NGW = G * NWAVES;
amdhsa.kernels:
  - .agpr_count:     0
    .args:
      - .offset:         0
        .size:           248
        .value_kind:     by_value
      - .offset:         248
        .size:           4
        .value_kind:     hidden_block_count_x
      - .offset:         252
        .size:           4
        .value_kind:     hidden_block_count_y
      - .offset:         256
        .size:           4
        .value_kind:     hidden_block_count_z
      - .offset:         260
        .size:           2
        .value_kind:     hidden_group_size_x
      - .offset:         262
        .size:           2
        .value_kind:     hidden_group_size_y
      - .offset:         264
        .size:           2
        .value_kind:     hidden_group_size_z
      - .offset:         266
        .size:           2
        .value_kind:     hidden_remainder_x
      - .offset:         268
        .size:           2
        .value_kind:     hidden_remainder_y
      - .offset:         270
        .size:           2
        .value_kind:     hidden_remainder_z
      - .offset:         288
        .size:           8
        .value_kind:     hidden_global_offset_x
      - .offset:         296
        .size:           8
        .value_kind:     hidden_global_offset_y
      - .offset:         304
        .size:           8
        .value_kind:     hidden_global_offset_z
      - .offset:         312
        .size:           2
        .value_kind:     hidden_grid_dims
      - .offset:         336
        .size:           8
        .value_kind:     hidden_multigrid_sync_arg
      - .offset:         368
        .size:           4
        .value_kind:     hidden_dynamic_lds_size
    .group_segment_fixed_size: 0
    .kernarg_segment_align: 8
    .kernarg_segment_size: 504
    .language:       OpenCL C
    .language_version:
      - 2
      - 0
    .max_flat_workgroup_size: 512
    .name:           _Z14fwd_megakernel5KArgs
    .private_segment_fixed_size: 0
    .sgpr_count:     106
    .sgpr_spill_count: 147
    .symbol:         _Z14fwd_megakernel5KArgs.kd
    .uniform_work_group_size: 1
    .uses_dynamic_stack: false
    .vgpr_count:     256
    .vgpr_spill_count: 0
    .wavefront_size: 64
